# row phases: non-temporal (nt) hint on the residual-stream row loads
# speedup vs baseline: 1.0029x; 1.0029x over previous
.LBB0_478:
	v_lshlrev_b64 v[82:83], 12, v[82:83]
	v_ashrrev_i32_e32 v86, 10, v130
	v_lshl_add_u64 v[82:83], v[84:85], 0, v[82:83]
	v_lshlrev_b32_e32 v130, 2, v98
	v_add_u32_e32 v86, 1, v86
	v_lshl_add_u64 v[82:83], v[82:83], 0, v[130:131]
	v_cndmask_b32_e64 v132, v86, 0, s[0:1]
	global_load_dwordx4 v[94:97], v[82:83], off nt
	global_load_dwordx4 v[90:93], v[82:83], off offset:1024 nt
	global_load_dwordx4 v[86:89], v[82:83], off offset:2048 nt
	s_nop 0
	global_load_dwordx4 v[82:85], v[82:83], off offset:3072 nt
	v_cndmask_b32_e64 v133, 0, 1, s[4:5]
	v_cmp_ne_u32_e64 s[0:1], 1, v133
	s_andn2_b64 vcc, exec, s[4:5]
	s_cbranch_vccnz .LBB0_480
	v_lshlrev_b64 v[10:11], 11, v[128:129]
	v_lshl_add_u64 v[42:43], v[100:101], 0, v[10:11]
	global_load_dwordx2 v[112:113], v[42:43], off
	v_add_u32_e32 v44, s20, v132
	global_load_dwordx2 v[116:117], v[42:43], off offset:512
	global_load_dwordx4 v[10:13], v[108:109], off
	global_load_dwordx4 v[26:29], v[108:109], off offset:1024
	global_load_dwordx2 v[120:121], v[42:43], off offset:1024
	global_load_dwordx4 v[38:41], v[108:109], off offset:2048
	global_load_dwordx4 v[74:77], v[108:109], off offset:3072
	v_mad_i64_i32 v[78:79], s[6:7], v44, s3, v[110:111]
	global_load_dwordx2 v[124:125], v[42:43], off offset:1536
	s_nop 0
	global_load_dwordx4 v[42:45], v[78:79], off
	global_load_dwordx4 v[54:57], v[78:79], off offset:1024
	global_load_dwordx4 v[66:69], v[78:79], off offset:2048
	s_nop 0
	global_load_dwordx4 v[78:81], v[78:79], off offset:3072
	s_waitcnt vmcnt(10)
	v_lshlrev_b32_e32 v118, 16, v116
	v_and_b32_e32 v119, 0xffff0000, v116
	v_lshlrev_b32_e32 v116, 16, v117
	v_lshlrev_b32_e32 v114, 16, v112
	v_and_b32_e32 v115, 0xffff0000, v112
	v_lshlrev_b32_e32 v112, 16, v113
	v_and_b32_e32 v113, 0xffff0000, v113
	v_and_b32_e32 v117, 0xffff0000, v117
	s_waitcnt vmcnt(7)
	v_lshlrev_b32_e32 v122, 16, v120
	v_and_b32_e32 v123, 0xffff0000, v120
	v_lshlrev_b32_e32 v120, 16, v121
	v_and_b32_e32 v121, 0xffff0000, v121
	s_waitcnt vmcnt(4)
	v_lshlrev_b32_e32 v126, 16, v124
	v_and_b32_e32 v127, 0xffff0000, v124
	v_lshlrev_b32_e32 v124, 16, v125
	v_and_b32_e32 v125, 0xffff0000, v125
